# grid-size guards: the kv unit remap and the unequal conversion split apply only on a 256-workgroup grid, otherwise the original assignment
# baseline (speedup 1.0000x reference)
.LBB0_44:
	s_or_b64 exec, exec, s[0:1]
	s_mov_b32 s97, s38
	s_lshl_b32 s0, s38, 3
	s_add_i32 s22, s0, s20
	v_readlane_b32 s98, v255, 2
	s_cmpk_lg_u32 s98, 0x100
	s_cbranch_scc1 .Lcv_orig
	s_cmpk_lt_u32 s38, 144
	s_cbranch_scc1 .Lcv_mod
	s_addk_i32 s22, -1152
	s_movk_i32 s98, 896
	s_mov_b32 s99, 30783
	s_branch .Lcv_go
.Lcv_mod:
	s_add_i32 s22, s22, 30784
	s_movk_i32 s98, 1152
	s_mov_b32 s99, 0x9c3f
	s_branch .Lcv_go
.Lcv_orig:
	s_lshl_b32 s98, s98, 3
	s_mov_b32 s99, 0x9c3f

.LBB0_418:
	s_add_u32 s94, s96, 0x19000000
	s_addc_u32 s95, s97, 0
	v_readlane_b32 s0, v255, 2
	s_add_u32 s38, s96, 0x1fc00000
	s_mov_b32 s24, s0
	v_readlane_b32 s3, v255, 4
	s_addc_u32 s39, s97, 0
	v_mov_b32_e32 v0, v181
	s_cmpk_lg_u32 s24, 0x100
	s_cbranch_scc1 .Lkv_noremap
	s_xor_b32 s3, s3, 0x80
.Lkv_noremap:
	s_cmpk_gt_i32 s3, 0x47f
	v_readfirstlane_b32 s4, v0
	v_readlane_b32 s1, v255, 3
	s_cbranch_scc1 .LBB0_432
	v_lshlrev_b32_e32 v1, 4, v0
	v_add_u32_e32 v2, 0x2000, v1
	v_ashrrev_i32_e32 v3, 31, v2
	v_lshrrev_b32_e32 v3, 22, v3
	v_add_u32_e32 v3, v2, v3
	v_ashrrev_i32_e32 v3, 10, v3
	v_mul_i32_i24_e32 v4, 0x400, v3
	v_sub_u32_e32 v2, v2, v4
	v_lshrrev_b32_e32 v4, 4, v2
	v_bitop3_b32 v2, v4, v2, 32 bitop3:0x6c
	v_readlane_b32 s0, v255, 13
	v_ashrrev_i32_e32 v4, 31, v2
	s_add_u32 s25, s96, 0x10000200
	v_readlane_b32 s1, v255, 14
	v_lshrrev_b32_e32 v4, 26, v4
	s_addc_u32 s26, s97, 0
	s_lshl_b64 s[0:1], s[0:1], 19
	v_add_u32_e32 v4, v2, v4
	v_lshlrev_b32_e32 v6, 3, v3
	s_add_u32 s0, s96, s0
	v_ashrrev_i32_e32 v5, 6, v4
	v_and_b32_e32 v6, -16, v6
	v_and_b32_e32 v4, 0xc0, v4
	s_addc_u32 s1, s97, s1
	v_add_u32_e32 v6, v5, v6
	v_sub_u32_e32 v2, v2, v4
	s_add_u32 s27, s0, 0xa000000
	v_and_b32_e32 v5, 3, v5
	s_mov_b32 s0, 0xffffe0
	v_lshrrev_b32_e32 v7, 2, v6
	v_lshlrev_b32_e32 v8, 1, v6
	v_lshlrev_b32_e32 v3, 5, v3
	v_ashrrev_i16_sdwa v2, v219, sext(v2) dst_sel:DWORD dst_unused:UNUSED_PAD src0_sel:DWORD src1_sel:BYTE_0
	v_and_or_b32 v5, v6, s0, v5
	v_and_b32_e32 v7, 4, v7
	v_and_b32_e32 v8, 24, v8
	v_and_b32_e32 v3, 32, v3
	v_bfe_i32 v2, v2, 0, 16
	v_or3_b32 v5, v5, v7, v8
	v_add_lshl_u32 v2, v3, v2, 1
	v_lshl_add_u32 v128, v5, 8, v2
	v_lshl_add_u32 v130, v6, 10, v2
	v_bfe_i32 v2, v0, 27, 1
	v_lshrrev_b32_e32 v2, 22, v2
	v_add_u32_e32 v2, v1, v2
	v_and_b32_e32 v2, 0xfffffc00, v2
	v_sub_u32_e32 v1, v1, v2
	v_lshrrev_b32_e32 v2, 4, v1
	v_ashrrev_i32_e32 v4, 31, v0
	v_bitop3_b32 v1, v2, v1, 32 bitop3:0x6c
	v_lshrrev_b32_e32 v4, 26, v4
	v_ashrrev_i32_e32 v2, 31, v1
	v_add_u32_e32 v4, v0, v4
	v_lshrrev_b32_e32 v2, 26, v2
	v_ashrrev_i32_e32 v4, 6, v4
	v_add_u32_e32 v2, v1, v2
	v_lshlrev_b32_e32 v5, 3, v4
	v_ashrrev_i32_e32 v3, 6, v2
	v_and_b32_e32 v5, -16, v5
	s_addc_u32 s28, s1, 0
	v_add_u32_e32 v5, v3, v5
	v_and_b32_e32 v3, 3, v3
	s_ashr_i32 s7, s3, 31
	v_and_or_b32 v3, v5, s0, v3
	s_lshr_b32 s0, s7, 29
	s_add_i32 s0, s3, s0
	s_ashr_i32 s5, s4, 6
	s_ashr_i32 s1, s0, 3
	s_and_b32 s0, s0, -8
	s_ashr_i32 s6, s4, 8
	s_lshl_b32 s29, s5, 10
	s_sub_i32 s0, s3, s0
	s_cmp_lt_i32 s0, 0
	s_movk_i32 s2, 0x91
	s_cselect_b32 s2, s2, 0x90
	s_mul_i32 s0, s0, s2
	s_add_i32 s0, s0, s1
	s_ashr_i32 s1, s0, 31
	s_lshr_b32 s1, s1, 26
	s_add_i32 s1, s0, s1
	s_ashr_i32 s2, s1, 6
	s_and_b32 s1, s1, 0xffc0
	s_sub_i32 s0, s0, s1
	s_bfe_i32 s1, s0, 0x80000
	s_bfe_u32 s1, s1, 0x3000c
	s_add_i32 s1, s0, s1
	s_lshl_b32 s8, s2, 3
	s_bfe_i32 s2, s1, 0x80000
	s_and_b32 s1, s1, 0xf8
	s_sub_i32 s0, s0, s1
	s_sext_i32_i16 s2, s2
	s_sext_i32_i8 s0, s0
	v_and_b32_e32 v2, 0xc0, v2
	s_lshr_b32 s2, s2, 3
	s_add_i32 s16, s8, s0
	v_sub_u32_e32 v1, v1, v2
	s_ashr_i32 s17, s16, 31
	s_bfe_i64 s[8:9], s[2:3], 0x100000
	v_lshrrev_b32_e32 v6, 2, v5
	v_lshlrev_b32_e32 v7, 1, v5
	v_lshlrev_b32_e32 v4, 5, v4
	v_ashrrev_i16_sdwa v1, v219, sext(v1) dst_sel:DWORD dst_unused:UNUSED_PAD src0_sel:DWORD src1_sel:BYTE_0
	s_lshl_b64 s[0:1], s[16:17], 18
	s_lshl_b64 s[8:9], s[8:9], 16
	v_and_b32_e32 v6, 4, v6
	v_and_b32_e32 v7, 24, v7
	v_and_b32_e32 v4, 32, v4
	v_bfe_i32 v1, v1, 0, 16
	s_add_u32 s18, s27, s8
	v_or3_b32 v3, v3, v6, v7
	v_add_lshl_u32 v1, v4, v1, 1
	s_addc_u32 s19, s28, s9
	s_add_i32 s43, s29, 0
	v_lshl_add_u32 v132, v3, 8, v1
	s_add_i32 m0, s43, 0x10000
	v_lshl_add_u32 v134, v5, 10, v1
	global_load_lds_dwordx4 v132, s[18:19]
	s_add_i32 m0, s43, 0x12000
	s_add_u32 s8, s18, 0x8000
	global_load_lds_dwordx4 v128, s[18:19]
	s_addc_u32 s9, s19, 0
	s_add_i32 m0, s43, 0x14000
	s_nop 0
	global_load_lds_dwordx4 v132, s[8:9]
	s_add_i32 m0, s43, 0x16000
	s_add_u32 s20, s25, s0
	s_addc_u32 s21, s26, s1
	s_add_i32 s44, s43, 0x2000
	global_load_lds_dwordx4 v128, s[8:9]
	s_mov_b32 m0, s43
	s_add_u32 s0, s20, 0x20000
	global_load_lds_dwordx4 v134, s[20:21]
	s_mov_b32 m0, s44
	s_addc_u32 s1, s21, 0
	s_add_i32 s50, s43, 0x4000
	global_load_lds_dwordx4 v130, s[20:21]
	s_mov_b32 m0, s50
	s_add_i32 s51, s43, 0x6000
	global_load_lds_dwordx4 v134, s[0:1]
	s_mov_b32 m0, s51
	s_cmp_eq_u32 s6, 1
	global_load_lds_dwordx4 v130, s[0:1]
	s_cselect_b64 s[0:1], -1, 0
	s_cmp_lg_u32 s6, 1
	s_cbranch_scc1 .LBB0_421
	s_barrier
